# max|q_norm_g| / max|k_norm_g| computed by wave 1 during grid barrier 1 and parked in LDS instead of eight dependent load rounds at the start of the attention phase
# baseline (speedup 1.0000x reference)
; __global__ void __launch_bounds__(NTHREADS, 2) fwd_megakernel(Args a) {
;     ...
;         float mq = 0.f, mk = 0.f;
;         for (int i = 0; i < 96; ++i) { mq = fmaxf(mq, fabsf(a.q_norm_g[i])); mk = fmaxf(mk, fabsf(a.k_norm_g[i])); }
;         const float mb = fminf(96.f * mq * mk * 0.10206207261596577f * LOG2E, 80.f);
.Lcen_done:
	v_bcnt_u32_b32 v4, v2, 0
	v_bcnt_u32_b32 v4, v3, v4
	v_cmp_eq_u32_e32 vcc, 1, v4
	s_nop 1
	s_mov_b64 s[100:101], vcc
	v_cmp_eq_u32_e32 vcc, 32, v1
	s_nop 1
	s_and_b64 s[100:101], s[100:101], vcc
	v_or_b32_e32 v4, v2, v3
	v_cmp_eq_u32_e32 vcc, 0, v4
	s_nop 1
	s_or_b64 s[100:101], s[100:101], vcc
	s_andn2_b64 s[100:101], exec, s[100:101]
	s_cmp_eq_u64 s[100:101], 0
	s_cselect_b32 s100, 1, 0
	v_mov_b32_e32 v0, 0x23030
	v_mov_b32_e32 v1, s100
	ds_write_b32 v0, v1
	s_waitcnt lgkmcnt(0)
	v_mbcnt_lo_u32_b32 v0, -1, 0
	v_mbcnt_hi_u32_b32 v0, -1, v0
	v_cmp_gt_u32_e32 vcc, 24, v0
	v_lshlrev_b32_e32 v1, 4, v0
	v_mov_b32_e32 v2, 0
	v_mov_b32_e32 v3, 0
	v_mov_b32_e32 v4, 0
	v_mov_b32_e32 v5, 0
	v_mov_b32_e32 v6, 0
	v_mov_b32_e32 v7, 0
	v_mov_b32_e32 v8, 0
	v_mov_b32_e32 v9, 0
	s_and_saveexec_b64 s[100:101], vcc
	global_load_dwordx4 v[2:5], v1, s[72:73]
	global_load_dwordx4 v[6:9], v1, s[74:75]
	s_or_b64 exec, exec, s[100:101]
	s_waitcnt vmcnt(0)
	v_max3_f32 v2, |v2|, |v3|, |v4|
	v_max_f32_e64 v2, v2, |v5|
	v_max3_f32 v6, |v6|, |v7|, |v8|
	v_max_f32_e64 v6, v6, |v9|
	s_nop 1
	v_max_f32_dpp v10, v2, v2 row_ror:8 row_mask:0xf bank_mask:0xf
	s_nop 1
	v_max_f32_dpp v11, v10, v10 row_ror:4 row_mask:0xf bank_mask:0xf
	s_nop 1
	v_max_f32_dpp v12, v11, v11 row_ror:2 row_mask:0xf bank_mask:0xf
	s_nop 1
	v_max_f32_dpp v2, v12, v12 row_ror:1 row_mask:0xf bank_mask:0xf
	s_nop 1
	v_max_f32_dpp v13, v6, v6 row_ror:8 row_mask:0xf bank_mask:0xf
	s_nop 1
	v_max_f32_dpp v14, v13, v13 row_ror:4 row_mask:0xf bank_mask:0xf
	s_nop 1
	v_max_f32_dpp v15, v14, v14 row_ror:2 row_mask:0xf bank_mask:0xf
	s_nop 1
	v_max_f32_dpp v6, v15, v15 row_ror:1 row_mask:0xf bank_mask:0xf
	s_nop 1
	v_readlane_b32 s98, v2, 0
	v_readlane_b32 s99, v2, 16
	v_readlane_b32 s100, v6, 0
	v_readlane_b32 s101, v6, 16
	v_mov_b32_e32 v2, s98
	v_max_f32_e32 v2, s99, v2
	v_mov_b32_e32 v3, s100
	v_max_f32_e32 v3, s101, v3
	v_mov_b32_e32 v0, 0x23034
	ds_write2_b32 v0, v2, v3 offset1:1
	s_waitcnt lgkmcnt(0)

; __global__ void __launch_bounds__(NTHREADS, 2) fwd_megakernel(Args a) {
;     ...
;         float mq = 0.f, mk = 0.f;
;         for (int i = 0; i < 96; ++i) { mq = fmaxf(mq, fabsf(a.q_norm_g[i])); mk = fmaxf(mk, fabsf(a.k_norm_g[i])); }
;         const float mb = fminf(96.f * mq * mk * 0.10206207261596577f * LOG2E, 80.f);
;         unsigned* s2cnt = (unsigned*)(ws + WS_BAR) + XCD_BAR_WORDS + 64;
;         p0b_mlp_weights(a, lds);
.LBB0_512:
	v_mov_b32_e32 v0, 0x23034
	ds_read2_b32 v[82:83], v0 offset1:1
	s_waitcnt lgkmcnt(0)
	s_add_u32 s10, s92, 0xf6a0000
	v_mov_b32_e32 v0, v210
	s_addc_u32 s11, s93, 0
	v_readlane_b32 s0, v241, 19
	v_ashrrev_i32_e32 v1, 6, v0
	s_add_u32 s50, s92, 0xeea0000
	v_add_u32_e32 v84, s0, v1
	v_add_u32_e32 v84, 0x400, v84
	s_movk_i32 s20, 0
	s_addc_u32 s51, s93, 0
	v_cmp_gt_i32_e32 vcc, s20, v84
	s_and_saveexec_b64 s[20:21], vcc
	v_readlane_b32 s64, v241, 2
	v_readlane_b32 s72, v241, 10
	v_readlane_b32 s73, v241, 11
	v_readlane_b32 s74, v241, 12
	v_readlane_b32 s75, v241, 13
	v_readlane_b32 s76, v241, 14
	v_readlane_b32 s77, v241, 15
	v_readlane_b32 s78, v241, 16
	v_readlane_b32 s79, v241, 17
	v_readlane_b32 s65, v241, 3
	v_readlane_b32 s66, v241, 4
	v_readlane_b32 s67, v241, 5
	v_readlane_b32 s68, v241, 6
	v_readlane_b32 s69, v241, 7
	v_readlane_b32 s70, v241, 8
	v_readlane_b32 s71, v241, 9
	s_cbranch_execz .LBB0_554
	s_movk_i32 s24, 0x4100
	v_mul_lo_u32 v2, v1, s24
	v_add_u32_e32 v3, 0, v2
	v_bfe_u32 v85, v0, 4, 2
	v_lshlrev_b32_e32 v2, 2, v0
	v_bfe_u32 v87, v0, 3, 3
	v_lshlrev_b32_e32 v0, 3, v0
	v_and_b32_e32 v6, 56, v0
	v_and_b32_e32 v86, 60, v2
	v_mul_u32_u24_e32 v0, 0x104, v6
	v_lshlrev_b32_e32 v7, 2, v87
	v_lshlrev_b32_e32 v2, 2, v86
	v_add3_u32 v88, v3, v0, v7
	v_mov_b32_e32 v0, 0
	v_readlane_b32 s0, v241, 18
	v_add_u32_e32 v4, v3, v2
	v_mul_u32_u24_e32 v5, 0x104, v85
	v_mov_b32_e32 v3, v0
	v_lshl_add_u32 v96, v1, 6, s0
	v_add_u32_e32 v96, 0x10000, v96
	v_lshlrev_b32_e32 v1, 2, v1
	s_cmp_lg_u64 s[72:73], 0
	v_lshl_add_u64 v[68:69], s[76:77], 0, v[2:3]
	v_lshl_add_u64 v[70:71], s[74:75], 0, v[2:3]
	v_lshlrev_b32_e32 v2, 1, v6
	v_lshl_add_u32 v1, s2, 5, v1
	v_add_u32_e32 v98, v4, v5
	s_mov_b64 s[22:23], 0
	s_cselect_b64 s[42:43], -1, 0
	v_or_b32_e32 v89, 8, v87
	v_or_b32_e32 v90, 16, v87
	v_or_b32_e32 v91, 24, v87
	v_or_b32_e32 v92, 32, v87
	v_or_b32_e32 v93, 40, v87
	v_or_b32_e32 v94, 48, v87
	v_or_b32_e32 v95, 56, v87
	v_lshl_add_u64 v[72:73], s[10:11], 0, v[2:3]
	v_lshl_add_u64 v[74:75], s[50:51], 0, v[2:3]
	v_add_u32_e32 v97, 0x40000, v1
	s_lshl_b32 s26, s94, 5
	v_add_u32_e32 v99, 0x410, v98
	v_add_u32_e32 v100, 0x418, v98
	v_add_u32_e32 v101, 0x820, v98
	v_add_u32_e32 v102, 0x828, v98
	v_add_u32_e32 v103, 0xc30, v98
	v_add_u32_e32 v104, 0xc38, v98
	v_add_u32_e32 v105, 0x1040, v98
	v_add_u32_e32 v106, 0x1048, v98
	v_add_u32_e32 v107, 0x1450, v98
	v_add_u32_e32 v108, 0x1458, v98
	v_add_u32_e32 v109, 0x1860, v98
	v_add_u32_e32 v110, 0x1868, v98
	v_add_u32_e32 v111, 0x1c70, v98
	v_add_u32_e32 v112, 0x1c78, v98
	v_add_u32_e32 v113, 0x2080, v98
	v_add_u32_e32 v114, 0x2088, v98
	v_add_u32_e32 v115, 0x2490, v98
	v_add_u32_e32 v116, 0x2498, v98
	v_add_u32_e32 v117, 0x28a0, v98
	v_add_u32_e32 v118, 0x28a8, v98
	v_add_u32_e32 v119, 0x2cb0, v98
	v_add_u32_e32 v120, 0x2cb8, v98
	v_add_u32_e32 v121, 0x30c0, v98
	v_add_u32_e32 v122, 0x30c8, v98
	v_add_u32_e32 v123, 0x34d0, v98
	s_branch .LBB0_517
